# baseline (speedup 1.0000x reference)
; #define SBAR() __builtin_amdgcn_sched_barrier(0)
; template <int D0> __device__ __forceinline__ void pv_one(f32x16& od, int vb, bf16x8 pa0, bf16x8 pa1, bf16x8 pa2, bf16x8 pa3) {
;   const s16x4 l0 = tr_read<v_rd_off(D0, 0, 0)>(vb), h0 = tr_read<v_rd_off(D0, 0, 1)>(vb), l1 = tr_read<v_rd_off(D0, 1, 0)>(vb), h1 = tr_read<v_rd_off(D0, 1, 1)>(vb);
;   const s16x4 l2 = tr_read<v_rd_off(D0, 2, 0)>(vb), h2 = tr_read<v_rd_off(D0, 2, 1)>(vb), l3 = tr_read<v_rd_off(D0, 3, 0)>(vb), h3 = tr_read<v_rd_off(D0, 3, 1)>(vb);
;   asm volatile("s_waitcnt lgkmcnt(0)" ::: "memory"); SBAR();
;     ...
;   od = __builtin_amdgcn_mfma_f32_32x32x16_bf16(pa0, PK(l0, h0), od, 0, 0, 0);
;   od = __builtin_amdgcn_mfma_f32_32x32x16_bf16(pa1, PK(l1, h1), od, 0, 0, 0);
;   od = __builtin_amdgcn_mfma_f32_32x32x16_bf16(pa2, PK(l2, h2), od, 0, 0, 0);
;   od = __builtin_amdgcn_mfma_f32_32x32x16_bf16(pa3, PK(l3, h3), od, 0, 0, 0);
.LBB0_244:
	v_add_u32_e32 v224, s10, v214
	ds_read_b64_tr_b16 v[166:167], v224 offset:0
	ds_read_b64_tr_b16 v[168:169], v224 offset:0x800
	ds_read_b64_tr_b16 v[170:171], v224 offset:0x1000
	ds_read_b64_tr_b16 v[172:173], v224 offset:0x1800
	ds_read_b64_tr_b16 v[174:175], v224 offset:0x2000
	ds_read_b64_tr_b16 v[176:177], v224 offset:0x2800
	ds_read_b64_tr_b16 v[178:179], v224 offset:0x3000
	ds_read_b64_tr_b16 v[180:181], v224 offset:0x3800
	s_waitcnt lgkmcnt(0)
	s_nop 0
	v_mfma_f32_32x32x16_bf16 v[0:15], v[146:149], v[166:169], v[0:15]
	ds_read_b64_tr_b16 v[166:167], v224 offset:0x200
	ds_read_b64_tr_b16 v[168:169], v224 offset:0xa00
	v_mfma_f32_32x32x16_bf16 v[0:15], v[150:153], v[170:173], v[0:15]
	ds_read_b64_tr_b16 v[170:171], v224 offset:0x1200
	ds_read_b64_tr_b16 v[172:173], v224 offset:0x1a00
	v_mfma_f32_32x32x16_bf16 v[0:15], v[154:157], v[174:177], v[0:15]
	ds_read_b64_tr_b16 v[174:175], v224 offset:0x2200
	ds_read_b64_tr_b16 v[176:177], v224 offset:0x2a00
	v_mfma_f32_32x32x16_bf16 v[0:15], v[158:161], v[178:181], v[0:15]
	ds_read_b64_tr_b16 v[178:179], v224 offset:0x3200
	ds_read_b64_tr_b16 v[180:181], v224 offset:0x3a00
	v_add_u32_e32 v130, 0xfffd0000, v227
	v_add_u32_e32 v134, 0xfffe0000, v227
	global_load_dwordx4 v[138:141], v130, s[8:9]
	s_nop 0
	global_load_dwordx4 v[130:133], v130, s[2:3]
	s_nop 0
	global_load_dwordx4 v[142:145], v134, s[8:9]
	s_nop 0
	global_load_dwordx4 v[134:137], v134, s[2:3]
	s_waitcnt vmcnt(4)
	v_add_u32_e32 v228, s4, v216
	ds_write_b128 v228, v[126:129]
	s_waitcnt lgkmcnt(1)
	v_mfma_f32_32x32x16_bf16 v[16:31], v[146:149], v[166:169], v[16:31]
	ds_read_b64_tr_b16 v[166:167], v224 offset:0x400
	ds_read_b64_tr_b16 v[168:169], v224 offset:0xc00
	v_mul_f32_e32 v196, 0xbe38aa3b, v213
	v_fmamk_f32 v80, v80, 0x3e38aa3b, v196
	v_fmamk_f32 v81, v81, 0x3e38aa3b, v196
	v_fmamk_f32 v82, v82, 0x3e38aa3b, v196
	v_mfma_f32_32x32x16_bf16 v[16:31], v[150:153], v[170:173], v[16:31]
	ds_read_b64_tr_b16 v[170:171], v224 offset:0x1400
	ds_read_b64_tr_b16 v[172:173], v224 offset:0x1c00
	v_fmamk_f32 v83, v83, 0x3e38aa3b, v196
	v_fmamk_f32 v84, v84, 0x3e38aa3b, v196
	v_fmamk_f32 v85, v85, 0x3e38aa3b, v196
	v_fmamk_f32 v86, v86, 0x3e38aa3b, v196
	v_mfma_f32_32x32x16_bf16 v[16:31], v[154:157], v[174:177], v[16:31]
	ds_read_b64_tr_b16 v[174:175], v224 offset:0x2400
	ds_read_b64_tr_b16 v[176:177], v224 offset:0x2c00
	v_fmamk_f32 v87, v87, 0x3e38aa3b, v196
	v_fmamk_f32 v88, v88, 0x3e38aa3b, v196
	v_fmamk_f32 v89, v89, 0x3e38aa3b, v196
	v_fmamk_f32 v90, v90, 0x3e38aa3b, v196
	v_mfma_f32_32x32x16_bf16 v[16:31], v[158:161], v[178:181], v[16:31]
	ds_read_b64_tr_b16 v[178:179], v224 offset:0x3400
	ds_read_b64_tr_b16 v[180:181], v224 offset:0x3c00
	v_fmamk_f32 v91, v91, 0x3e38aa3b, v196
	v_fmamk_f32 v92, v92, 0x3e38aa3b, v196
	v_fmamk_f32 v93, v93, 0x3e38aa3b, v196
	v_fmamk_f32 v94, v94, 0x3e38aa3b, v196
	v_add_u32_e32 v228, s4, v217
	ds_write_b128 v228, v[122:125]
	s_waitcnt lgkmcnt(1)
	v_mfma_f32_32x32x16_bf16 v[32:47], v[146:149], v[166:169], v[32:47]
	ds_read_b64_tr_b16 v[166:167], v224 offset:0x600
	ds_read_b64_tr_b16 v[168:169], v224 offset:0xe00
	v_fmamk_f32 v95, v95, 0x3e38aa3b, v196
	v_fmamk_f32 v197, v70, 0x3e38aa3b, v196
	v_fmamk_f32 v198, v71, 0x3e38aa3b, v196
	v_fmamk_f32 v199, v72, 0x3e38aa3b, v196
	v_mfma_f32_32x32x16_bf16 v[32:47], v[150:153], v[170:173], v[32:47]
	ds_read_b64_tr_b16 v[170:171], v224 offset:0x1600
	ds_read_b64_tr_b16 v[172:173], v224 offset:0x1e00
	v_fmamk_f32 v200, v73, 0x3e38aa3b, v196
	v_fmamk_f32 v201, v74, 0x3e38aa3b, v196
	v_fmamk_f32 v202, v75, 0x3e38aa3b, v196
	v_fmamk_f32 v203, v76, 0x3e38aa3b, v196
	v_mfma_f32_32x32x16_bf16 v[32:47], v[154:157], v[174:177], v[32:47]
	ds_read_b64_tr_b16 v[174:175], v224 offset:0x2600
	ds_read_b64_tr_b16 v[176:177], v224 offset:0x2e00
	v_fmamk_f32 v204, v77, 0x3e38aa3b, v196
	v_fmamk_f32 v205, v78, 0x3e38aa3b, v196
	v_mfma_f32_32x32x16_bf16 v[32:47], v[158:161], v[178:181], v[32:47]
	ds_read_b64_tr_b16 v[178:179], v224 offset:0x3600
	ds_read_b64_tr_b16 v[180:181], v224 offset:0x3e00
	v_add_u32_e32 v228, s4, v221
	ds_write_b128 v228, v[118:121] offset:49152
	s_waitcnt lgkmcnt(1)
	v_mfma_f32_32x32x16_bf16 v[48:63], v[146:149], v[166:169], v[48:63]
	v_add_u32_e32 v228, s4, v222
	ds_write_b128 v228, v[114:117] offset:49152
	v_exp_f32_e32 v146, v80
	v_exp_f32_e32 v147, v81
	v_exp_f32_e32 v148, v84
	v_exp_f32_e32 v149, v85
	v_mfma_f32_32x32x16_bf16 v[48:63], v[150:153], v[170:173], v[48:63]
	v_exp_f32_e32 v150, v88
	v_exp_f32_e32 v151, v89
	v_exp_f32_e32 v152, v92
	v_exp_f32_e32 v153, v93
	v_mfma_f32_32x32x16_bf16 v[48:63], v[154:157], v[174:177], v[48:63]
	v_exp_f32_e32 v154, v94
	v_exp_f32_e32 v155, v95
	v_exp_f32_e32 v156, v90
	v_exp_f32_e32 v157, v91
	v_fmamk_f32 v174, v64, 0x3e38aa3b, v196
	v_fmamk_f32 v175, v65, 0x3e38aa3b, v196
	v_mfma_f32_32x32x16_bf16 v[48:63], v[158:161], v[178:181], v[48:63]
	v_exp_f32_e32 v158, v86
	v_exp_f32_e32 v159, v87
	v_exp_f32_e32 v160, v82
	v_exp_f32_e32 v161, v83
	v_fmamk_f32 v178, v66, 0x3e38aa3b, v196
	v_fmamk_f32 v179, v67, 0x3e38aa3b, v196
	v_fmamk_f32 v180, v68, 0x3e38aa3b, v196
	v_fmamk_f32 v181, v69, 0x3e38aa3b, v196
	v_fmac_f32_e32 v196, 0x3e38aa3b, v79
	s_waitcnt lgkmcnt(0)
	s_barrier
; __device__ __forceinline__ void da_qkt(f32x16& p0, f32x16& p1, const char* Ks, const bf16x8* qr, int r32, int hi, int cbyte0) {
;   p0 = f32x16{}; p1 = f32x16{};
; #pragma unroll
;   for (int d0 = 0; d0 < 4; ++d0) {
;     int cbb = cbyte0 + (d0 * 16 + hi * 8) * 2;
;     bf16x8 b0 = *(const bf16x8*)(Ks + KSWZ(r32, cbb));
;     bf16x8 b1 = *(const bf16x8*)(Ks + KSWZ(32 + r32, cbb));
;     p0 = __builtin_amdgcn_mfma_f32_32x32x16_bf16(b0, qr[d0], p0, 0, 0, 0);
;     p1 = __builtin_amdgcn_mfma_f32_32x32x16_bf16(b1, qr[d0], p1, 0, 0, 0);
;   }
; __device__ __forceinline__ void da_finish2(f32x16& p0, f32x16& p1, float& m_reg, float& l_reg, float& alpha,
;                                            bf16x8& pa0, bf16x8& pa1, bf16x8& pa2, bf16x8& pa3) {
;   constexpr float C = DA_SCALE * 1.4426950408889634f;
; #pragma unroll
;   for (int r = 0; r < 16; ++r) p1[r] = __builtin_amdgcn_exp2f(p1[r]);
;   float ps = 0.f;
; #pragma unroll
;   for (int r = 0; r < 16; ++r) ps += p0[r];
; #pragma unroll
;   for (int r = 0; r < 16; ++r) ps += p1[r];
;   { auto rr = __builtin_amdgcn_permlane32_swap(__float_as_uint(ps), __float_as_uint(ps), false, false);
;     ps = __uint_as_float(rr[0]) + __uint_as_float(rr[1]); }
;   alpha = 1.f;
;   if (__builtin_expect(!__all(ps < DA_BIG), 0)) {
	v_add_u32_e32 v68, s4, v223
	ds_read_b128 v[64:67], v68 offset:49152
	ds_read_b128 v[68:71], v68 offset:57344
	v_add_u32_e32 v170, s4, v220
	ds_read_b128 v[166:169], v170 offset:49152
	ds_read_b128 v[170:173], v170 offset:57344
	v_exp_f32_e32 v176, v174
	s_waitcnt lgkmcnt(3)
	v_mfma_f32_32x32x16_bf16 v[80:95], v[64:67], v[110:113], 0
	v_exp_f32_e32 v177, v175
	v_exp_f32_e32 v182, v178
	v_exp_f32_e32 v183, v179
	v_exp_f32_e32 v180, v180
	v_exp_f32_e32 v181, v181
	v_exp_f32_e32 v178, v197
	v_exp_f32_e32 v179, v198
	s_waitcnt lgkmcnt(2)
	v_mfma_f32_32x32x16_bf16 v[64:79], v[68:71], v[110:113], 0
	v_exp_f32_e32 v174, v199
	v_exp_f32_e32 v175, v200
	s_waitcnt lgkmcnt(1)
	v_mfma_f32_32x32x16_bf16 v[80:95], v[166:169], v[106:109], v[80:95]
	s_waitcnt lgkmcnt(0)
	v_mfma_f32_32x32x16_bf16 v[64:79], v[170:173], v[106:109], v[64:79]
	v_add_u32_e32 v170, s4, v219
	ds_read_b128 v[166:169], v170 offset:49152
	ds_read_b128 v[170:173], v170 offset:57344
	s_waitcnt lgkmcnt(1)
	v_mfma_f32_32x32x16_bf16 v[80:95], v[166:169], v[102:105], v[80:95]
	s_waitcnt lgkmcnt(0)
	v_mfma_f32_32x32x16_bf16 v[64:79], v[170:173], v[102:105], v[64:79]
	v_add_u32_e32 v170, s4, v218
	ds_read_b128 v[166:169], v170 offset:49152
	ds_read_b128 v[170:173], v170 offset:57344
	s_waitcnt lgkmcnt(1)
	v_mfma_f32_32x32x16_bf16 v[80:95], v[166:169], v[98:101], v[80:95]
	v_add_f32_e32 v166, 0, v146
	v_add_f32_e32 v166, v147, v166
	v_add_f32_e32 v166, v160, v166
	v_add_f32_e32 v166, v161, v166
	v_add_f32_e32 v166, v148, v166
	v_add_f32_e32 v166, v149, v166
	v_add_f32_e32 v166, v158, v166
	v_add_f32_e32 v166, v159, v166
	v_add_f32_e32 v166, v150, v166
	v_add_f32_e32 v166, v151, v166
	v_add_f32_e32 v166, v156, v166
	v_add_f32_e32 v166, v157, v166
	v_add_f32_e32 v166, v152, v166
	v_add_f32_e32 v166, v153, v166
	v_add_f32_e32 v166, v154, v166
	v_add_f32_e32 v166, v155, v166
	v_add_f32_e32 v166, v176, v166
	v_add_f32_e32 v166, v177, v166
	v_add_f32_e32 v166, v182, v166
	v_add_f32_e32 v166, v183, v166
	v_add_f32_e32 v166, v180, v166
	v_add_f32_e32 v166, v181, v166
	s_waitcnt lgkmcnt(0)
	v_mfma_f32_32x32x16_bf16 v[64:79], v[170:173], v[98:101], v[64:79]
	v_exp_f32_e32 v172, v201
	v_add_f32_e32 v166, v178, v166
	v_exp_f32_e32 v173, v202
	v_add_f32_e32 v166, v179, v166
	v_exp_f32_e32 v170, v203
	v_add_f32_e32 v166, v174, v166
	v_exp_f32_e32 v171, v204
	v_add_f32_e32 v166, v175, v166
	v_exp_f32_e32 v168, v205
	v_add_f32_e32 v166, v172, v166
	v_exp_f32_e32 v169, v196
	v_add_f32_e32 v166, v173, v166
	v_add_f32_e32 v166, v170, v166
	v_add_f32_e32 v166, v171, v166
	v_add_f32_e32 v166, v168, v166
	v_add_f32_e32 v166, v169, v166
	v_mov_b32_e32 v167, v166
	s_nop 1
	v_permlane32_swap_b32_e32 v166, v167
	v_add_f32_e32 v225, v166, v167
	v_cmp_gt_f32_e32 vcc, s34, v225
	s_cmp_eq_u64 vcc, exec
	s_cbranch_scc0 .LBB0_255
	v_mov_b32_e32 v166, 1.0
